# grid barrier: the first arriver of each XCD issues an extra buffer_wbl2 right after arriving (early L2 write-back overlapping the stragglers)
# baseline (speedup 1.0000x reference)
.LBB0_279:
	s_or_b64 exec, exec, s[8:9]
	v_cvt_f32_u32_e32 v5, v3
	s_waitcnt vmcnt(0)
	v_readfirstlane_b32 s2, v4
	v_sub_u32_e32 v4, 0, v3
	v_rcp_iflag_f32_e32 v5, v5
	v_add_u32_e32 v6, s2, v2
	v_mul_f32_e32 v5, 0x4f7ffffe, v5
	v_cvt_u32_f32_e32 v5, v5
	v_mul_lo_u32 v2, v4, v5
	v_mul_hi_u32 v2, v5, v2
	v_add_u32_e32 v2, v5, v2
	v_mul_hi_u32 v2, v6, v2
	v_mul_lo_u32 v4, v2, v3
	v_sub_u32_e32 v4, v6, v4
	v_add_u32_e32 v5, 1, v2
	v_cmp_ge_u32_e32 vcc, v4, v3
	s_nop 1
	v_cndmask_b32_e32 v2, v2, v5, vcc
	v_sub_u32_e32 v5, v4, v3
	v_cndmask_b32_e32 v4, v4, v5, vcc
	v_add_u32_e32 v5, 1, v2
	v_cmp_ge_u32_e32 vcc, v4, v3
	v_add_u32_e32 v4, 1, v6
	s_nop 0
	v_cndmask_b32_e32 v2, v2, v5, vcc
	v_mul_lo_u32 v5, v3, v2
	v_add_u32_e32 v3, v5, v3
	v_cmp_ne_u32_e32 vcc, v4, v3
	s_and_saveexec_b64 s[6:7], vcc
	s_xor_b64 s[6:7], exec, s[6:7]
	s_cbranch_execz .LBB0_293
	v_cmp_eq_u32_e32 vcc, v6, v5
	s_nop 1
	s_cbranch_vccz .Lmy_wb_skip1
	buffer_wbl2 sc1
.Lmy_wb_skip1:
	s_waitcnt lgkmcnt(0)
	v_mov_b32_e32 v1, 0x7500
	global_load_dword v1, v1, s[86:87] sc1
	s_add_u32 s12, s86, 0x7500
	s_addc_u32 s13, s87, 0
	s_waitcnt vmcnt(0)
	v_cmp_eq_u32_e32 vcc, v1, v2
	s_and_saveexec_b64 s[8:9], vcc
	s_cbranch_execz .LBB0_292
	s_add_u32 s10, s86, 0x4200
	s_addc_u32 s11, s87, 0
	s_mov_b32 s2, 1
	s_mov_b64 s[16:17], 0
	v_mov_b32_e32 v1, 0
	s_branch .LBB0_283

.LBB0_373:
	s_or_b64 exec, exec, s[36:37]
	v_cvt_f32_u32_e32 v6, v4
	s_waitcnt vmcnt(0)
	v_readfirstlane_b32 s2, v5
	v_sub_u32_e32 v5, 0, v4
	v_rcp_iflag_f32_e32 v6, v6
	v_add_u32_e32 v7, s2, v3
	v_mul_f32_e32 v6, 0x4f7ffffe, v6
	v_cvt_u32_f32_e32 v6, v6
	v_mul_lo_u32 v3, v5, v6
	v_mul_hi_u32 v3, v6, v3
	v_add_u32_e32 v3, v6, v3
	v_mul_hi_u32 v3, v7, v3
	v_mul_lo_u32 v5, v3, v4
	v_sub_u32_e32 v5, v7, v5
	v_add_u32_e32 v6, 1, v3
	v_cmp_ge_u32_e32 vcc, v5, v4
	s_nop 1
	v_cndmask_b32_e32 v3, v3, v6, vcc
	v_sub_u32_e32 v6, v5, v4
	v_cndmask_b32_e32 v5, v5, v6, vcc
	v_add_u32_e32 v6, 1, v3
	v_cmp_ge_u32_e32 vcc, v5, v4
	v_add_u32_e32 v5, 1, v7
	s_nop 0
	v_cndmask_b32_e32 v3, v3, v6, vcc
	v_mul_lo_u32 v6, v4, v3
	v_add_u32_e32 v4, v6, v4
	v_cmp_ne_u32_e32 vcc, v5, v4
	s_and_saveexec_b64 s[8:9], vcc
	s_xor_b64 s[36:37], exec, s[8:9]
	s_cbranch_execz .LBB0_387
	v_cmp_eq_u32_e32 vcc, v7, v6
	s_nop 1
	s_cbranch_vccz .Lmy_wb_skip2
	buffer_wbl2 sc1
.Lmy_wb_skip2:
	v_readlane_b32 s8, v251, 30
	v_readlane_b32 s9, v251, 31
	s_waitcnt lgkmcnt(0)
	s_nop 3
	global_load_dword v2, v99, s[8:9] sc1
	s_waitcnt vmcnt(0)
	v_cmp_eq_u32_e32 vcc, v2, v3
	s_and_saveexec_b64 s[38:39], vcc
	s_cbranch_execz .LBB0_386
	s_mov_b32 s2, 1
	s_mov_b64 s[40:41], 0
	s_branch .LBB0_377

.LBB0_587:
	s_or_b64 exec, exec, s[22:23]
	v_cvt_f32_u32_e32 v6, v4
	s_waitcnt vmcnt(0)
	v_readfirstlane_b32 s4, v5
	v_sub_u32_e32 v5, 0, v4
	v_rcp_iflag_f32_e32 v6, v6
	v_add_u32_e32 v7, s4, v3
	v_mul_f32_e32 v6, 0x4f7ffffe, v6
	v_cvt_u32_f32_e32 v6, v6
	v_mul_lo_u32 v3, v5, v6
	v_mul_hi_u32 v3, v6, v3
	v_add_u32_e32 v3, v6, v3
	v_mul_hi_u32 v3, v7, v3
	v_mul_lo_u32 v5, v3, v4
	v_sub_u32_e32 v5, v7, v5
	v_add_u32_e32 v6, 1, v3
	v_cmp_ge_u32_e32 vcc, v5, v4
	s_nop 1
	v_cndmask_b32_e32 v3, v3, v6, vcc
	v_sub_u32_e32 v6, v5, v4
	v_cndmask_b32_e32 v5, v5, v6, vcc
	v_add_u32_e32 v6, 1, v3
	v_cmp_ge_u32_e32 vcc, v5, v4
	v_add_u32_e32 v5, 1, v7
	s_nop 0
	v_cndmask_b32_e32 v3, v3, v6, vcc
	v_mul_lo_u32 v6, v4, v3
	v_add_u32_e32 v4, v6, v4
	v_cmp_ne_u32_e32 vcc, v5, v4
	s_and_saveexec_b64 s[8:9], vcc
	s_xor_b64 s[22:23], exec, s[8:9]
	s_cbranch_execz .LBB0_601
	v_cmp_eq_u32_e32 vcc, v7, v6
	s_nop 1
	s_cbranch_vccz .Lmy_wb_skip3
	buffer_wbl2 sc1
.Lmy_wb_skip3:
	v_readlane_b32 s8, v251, 30
	v_readlane_b32 s9, v251, 31
	s_waitcnt lgkmcnt(0)
	s_nop 3
	global_load_dword v2, v99, s[8:9] sc1
	s_waitcnt vmcnt(0)
	v_cmp_eq_u32_e32 vcc, v2, v3
	s_and_saveexec_b64 s[36:37], vcc
	s_cbranch_execz .LBB0_600
	s_mov_b32 s4, 1
	s_mov_b64 s[38:39], 0
	s_branch .LBB0_591

.LBB0_1213:
	s_or_b64 exec, exec, s[22:23]
	v_cvt_f32_u32_e32 v6, v4
	s_waitcnt vmcnt(0)
	v_readfirstlane_b32 s2, v5
	v_sub_u32_e32 v5, 0, v4
	v_rcp_iflag_f32_e32 v6, v6
	v_add_u32_e32 v7, s2, v3
	v_mul_f32_e32 v6, 0x4f7ffffe, v6
	v_cvt_u32_f32_e32 v6, v6
	v_mul_lo_u32 v3, v5, v6
	v_mul_hi_u32 v3, v6, v3
	v_add_u32_e32 v3, v6, v3
	v_mul_hi_u32 v3, v7, v3
	v_mul_lo_u32 v5, v3, v4
	v_sub_u32_e32 v5, v7, v5
	v_add_u32_e32 v6, 1, v3
	v_cmp_ge_u32_e32 vcc, v5, v4
	s_nop 1
	v_cndmask_b32_e32 v3, v3, v6, vcc
	v_sub_u32_e32 v6, v5, v4
	v_cndmask_b32_e32 v5, v5, v6, vcc
	v_add_u32_e32 v6, 1, v3
	v_cmp_ge_u32_e32 vcc, v5, v4
	v_add_u32_e32 v5, 1, v7
	s_nop 0
	v_cndmask_b32_e32 v3, v3, v6, vcc
	v_mul_lo_u32 v6, v4, v3
	v_add_u32_e32 v4, v6, v4
	v_cmp_ne_u32_e32 vcc, v5, v4
	s_and_saveexec_b64 s[8:9], vcc
	s_xor_b64 s[22:23], exec, s[8:9]
	s_cbranch_execz .LBB0_1227
	v_cmp_eq_u32_e32 vcc, v7, v6
	s_nop 1
	s_cbranch_vccz .Lmy_wb_skip6
	buffer_wbl2 sc1
.Lmy_wb_skip6:
	v_readlane_b32 s8, v251, 30
	v_readlane_b32 s9, v251, 31
	s_waitcnt lgkmcnt(0)
	s_nop 3
	global_load_dword v2, v99, s[8:9] sc1
	s_waitcnt vmcnt(0)
	v_cmp_eq_u32_e32 vcc, v2, v3
	s_and_saveexec_b64 s[36:37], vcc
	s_cbranch_execz .LBB0_1226
	s_mov_b32 s2, 1
	s_mov_b64 s[38:39], 0
	s_branch .LBB0_1217

.LBB0_1271:
	s_or_b64 exec, exec, s[36:37]
	v_cvt_f32_u32_e32 v6, v4
	s_waitcnt vmcnt(0)
	v_readfirstlane_b32 s4, v5
	v_sub_u32_e32 v5, 0, v4
	v_rcp_iflag_f32_e32 v6, v6
	v_add_u32_e32 v7, s4, v3
	v_mul_f32_e32 v6, 0x4f7ffffe, v6
	v_cvt_u32_f32_e32 v6, v6
	v_mul_lo_u32 v3, v5, v6
	v_mul_hi_u32 v3, v6, v3
	v_add_u32_e32 v3, v6, v3
	v_mul_hi_u32 v3, v7, v3
	v_mul_lo_u32 v5, v3, v4
	v_sub_u32_e32 v5, v7, v5
	v_add_u32_e32 v6, 1, v3
	v_cmp_ge_u32_e32 vcc, v5, v4
	s_nop 1
	v_cndmask_b32_e32 v3, v3, v6, vcc
	v_sub_u32_e32 v6, v5, v4
	v_cndmask_b32_e32 v5, v5, v6, vcc
	v_add_u32_e32 v6, 1, v3
	v_cmp_ge_u32_e32 vcc, v5, v4
	v_add_u32_e32 v5, 1, v7
	s_nop 0
	v_cndmask_b32_e32 v3, v3, v6, vcc
	v_mul_lo_u32 v6, v4, v3
	v_add_u32_e32 v4, v6, v4
	v_cmp_ne_u32_e32 vcc, v5, v4
	s_and_saveexec_b64 s[8:9], vcc
	s_xor_b64 s[36:37], exec, s[8:9]
	s_cbranch_execz .LBB0_1285
	v_cmp_eq_u32_e32 vcc, v7, v6
	s_nop 1
	s_cbranch_vccz .Lmy_wb_skip7
	buffer_wbl2 sc1
.Lmy_wb_skip7:
	v_readlane_b32 s8, v251, 30
	v_readlane_b32 s9, v251, 31
	s_waitcnt lgkmcnt(0)
	s_nop 3
	global_load_dword v2, v99, s[8:9] sc1
	s_waitcnt vmcnt(0)
	v_cmp_eq_u32_e32 vcc, v2, v3
	s_and_saveexec_b64 s[38:39], vcc
	s_cbranch_execz .LBB0_1284
	s_mov_b32 s4, 1
	s_mov_b64 s[40:41], 0
	s_branch .LBB0_1275
